# stack7: stack6 + P5 sample path: split-K partial stores written through (sc1), group barrier without L2 writeback, early invalidate, one barrier fewer
# baseline (speedup 1.0000x reference)
.LBB0_723:
	s_add_u32 s2, s66, 0x11000000
	s_addc_u32 s3, s67, 0
	s_lshl_b32 s0, s15, 22
	s_add_u32 s6, s2, s0
	s_addc_u32 s7, s3, 0
	s_lshl_b32 s0, s4, 8
	s_addk_i32 s0, 0xc000
	v_or_b32_e32 v128, s0, v128
	v_add_u32_e32 v130, s5, v128
	v_lshl_or_b32 v128, s1, 8, v129
	v_ashrrev_i32_e32 v131, 31, v130
	v_or_b32_e32 v134, s16, v128
	v_lshlrev_b64 v[128:129], 12, v[130:131]
	v_lshl_add_u64 v[132:133], s[6:7], 0, v[128:129]
	v_lshlrev_b32_e32 v128, 2, v134
	v_mov_b32_e32 v129, 0
	v_lshl_add_u64 v[132:133], v[132:133], 0, v[128:129]
	global_store_dwordx4 v[132:133], v[40:43], off sc1
	global_store_dwordx4 v[132:133], v[44:47], off offset:16 sc1
	global_store_dwordx4 v[132:133], v[88:91], off offset:512 sc1
	global_store_dwordx4 v[132:133], v[92:95], off offset:528 sc1
	v_or_b32_e32 v40, 16, v130
	v_ashrrev_i32_e32 v41, 31, v40
	v_lshlrev_b64 v[40:41], 12, v[40:41]
	v_lshl_add_u64 v[40:41], s[6:7], 0, v[40:41]
	v_lshl_add_u64 v[40:41], v[40:41], 0, v[128:129]
	global_store_dwordx4 v[40:41], v[16:19], off sc1
	global_store_dwordx4 v[40:41], v[20:23], off offset:16 sc1
	global_store_dwordx4 v[40:41], v[64:67], off offset:512 sc1
	global_store_dwordx4 v[40:41], v[68:71], off offset:528 sc1
	v_or_b32_e32 v16, 32, v130
	v_ashrrev_i32_e32 v17, 31, v16
	v_lshlrev_b64 v[16:17], 12, v[16:17]
	v_lshl_add_u64 v[16:17], s[6:7], 0, v[16:17]
	v_lshl_add_u64 v[16:17], v[16:17], 0, v[128:129]
	global_store_dwordx4 v[16:17], v[8:11], off sc1
	global_store_dwordx4 v[16:17], v[12:15], off offset:16 sc1
	global_store_dwordx4 v[16:17], v[48:51], off offset:512 sc1
	global_store_dwordx4 v[16:17], v[56:59], off offset:528 sc1
	v_or_b32_e32 v8, 48, v130
	v_ashrrev_i32_e32 v9, 31, v8
	v_lshlrev_b64 v[8:9], 12, v[8:9]
	v_lshl_add_u64 v[8:9], s[6:7], 0, v[8:9]
	v_lshl_add_u64 v[8:9], v[8:9], 0, v[128:129]
	s_mov_b64 s[0:1], 0x80000
	global_store_dwordx4 v[8:9], v[0:3], off sc1
	global_store_dwordx4 v[8:9], v[4:7], off offset:16 sc1
	global_store_dwordx4 v[8:9], v[24:27], off offset:512 sc1
	global_store_dwordx4 v[8:9], v[32:35], off offset:528 sc1
	v_lshl_add_u64 v[0:1], v[132:133], 0, s[0:1]
	s_mov_b32 s0, 0x80000
	v_add_co_u32_e32 v2, vcc, s0, v132
	s_mov_b64 s[0:1], 0x90000
	s_nop 0
	v_addc_co_u32_e32 v3, vcc, 0, v133, vcc
	global_store_dwordx4 v[2:3], v[96:99], off sc1
	global_store_dwordx4 v[0:1], v[100:103], off offset:16 sc1
	global_store_dwordx4 v[0:1], v[120:123], off offset:512 sc1
	global_store_dwordx4 v[0:1], v[124:127], off offset:528 sc1
	v_lshl_add_u64 v[0:1], v[132:133], 0, s[0:1]
	s_mov_b32 s0, 0x90000
	v_add_co_u32_e32 v2, vcc, s0, v132
	s_mov_b64 s[0:1], 0xa0000
	s_nop 0
	v_addc_co_u32_e32 v3, vcc, 0, v133, vcc
	global_store_dwordx4 v[2:3], v[72:75], off sc1
	global_store_dwordx4 v[0:1], v[76:79], off offset:16 sc1
	global_store_dwordx4 v[0:1], v[112:115], off offset:512 sc1
	global_store_dwordx4 v[0:1], v[116:119], off offset:528 sc1
	v_lshl_add_u64 v[0:1], v[132:133], 0, s[0:1]
	s_mov_b32 s0, 0xa0000
	v_add_co_u32_e32 v2, vcc, s0, v132
	s_mov_b64 s[0:1], 0xb0000
	s_nop 0
	v_addc_co_u32_e32 v3, vcc, 0, v133, vcc
	global_store_dwordx4 v[2:3], v[52:55], off sc1
	global_store_dwordx4 v[0:1], v[60:63], off offset:16 sc1
	global_store_dwordx4 v[0:1], v[104:107], off offset:512 sc1
	global_store_dwordx4 v[0:1], v[108:111], off offset:528 sc1
	v_add_co_u32_e32 v2, vcc, 0xb0000, v132
	v_lshl_add_u64 v[0:1], v[132:133], 0, s[0:1]
	s_nop 0
	v_addc_co_u32_e32 v3, vcc, 0, v133, vcc
	global_store_dwordx4 v[2:3], v[28:31], off sc1
	global_store_dwordx4 v[0:1], v[36:39], off offset:16 sc1
	global_store_dwordx4 v[0:1], v[80:83], off offset:512 sc1
	global_store_dwordx4 v[0:1], v[84:87], off offset:528 sc1
	s_and_b64 vcc, exec, s[72:73]
	s_waitcnt vmcnt(0)
	s_barrier
	s_cbranch_vccnz .LBB0_742
	v_mbcnt_lo_u32_b32 v0, -1, 0
	v_mbcnt_hi_u32_b32 v0, -1, v0
	s_nop 0
	v_cmp_eq_u32_e32 vcc, 0, v0
	s_and_saveexec_b64 s[0:1], vcc
	s_cbranch_execz .LBB0_741
	s_lshl_b32 s4, s14, 6
	s_ashr_i32 s5, s4, 31
	s_lshl_b64 s[4:5], s[4:5], 2
	s_mov_b64 s[6:7], exec
	s_add_u32 s4, s66, s4
	s_addc_u32 s5, s67, s5
	v_mbcnt_lo_u32_b32 v0, s6, 0
	s_add_u32 s4, s4, 0x8000
	v_mbcnt_hi_u32_b32 v0, s7, v0
	s_addc_u32 s5, s5, 0
	v_cmp_eq_u32_e32 vcc, 0, v0
	s_and_saveexec_b64 s[8:9], vcc
	s_cbranch_execz .LBB0_727
	s_bcnt1_i32_b64 s6, s[6:7]
	v_mov_b32_e32 v0, 0
	v_mov_b32_e32 v1, s6
	global_atomic_add v0, v1, s[4:5]
.LBB0_727:
	s_or_b64 exec, exec, s[8:9]
	v_mov_b32_e32 v0, 0
	buffer_inv sc1
	global_load_dword v1, v0, s[4:5] sc1
	s_waitcnt vmcnt(0)
	v_cmp_lt_u32_e32 vcc, 15, v1
	s_cbranch_vccnz .LBB0_740
	s_mov_b32 s12, 1
	s_branch .LBB0_730

.LBB0_740:
	s_waitcnt vmcnt(0)
.LBB0_741:
	s_or_b64 exec, exec, s[0:1]
